# fused hand-off polls: s_sleep 4 -> s_sleep 1 between counter polls; on v36
# baseline (speedup 1.0000x reference)
.Lpanel_poll:
	global_load_dword v85, v84, s[90:91] sc1
	s_waitcnt vmcnt(0)
	v_readfirstlane_b32 s17, v85
	s_cmp_ge_u32 s17, s19
	s_cbranch_scc1 .Lpanel_ready
	s_sleep 1
	s_add_u32 s18, s18, 1
	s_cmp_lt_u32 s18, 0x1000
	s_cbranch_scc1 .Lpanel_poll

.Ltail_poll:
	global_load_dword v3, v2, s[90:91] sc1
	s_waitcnt vmcnt(0)
	v_readfirstlane_b32 s16, v3
	s_cmp_ge_u32 s16, s17
	s_cbranch_scc1 .Ltail_ready
	s_sleep 1
	s_add_u32 s18, s18, 1
	s_cmp_lt_u32 s18, 0x1000
	s_cbranch_scc1 .Ltail_poll
